# peel first FFN-in K iteration: accumulators start from inline 0 instead of 128 v_mov per tile
# speedup vs baseline: 1.0053x; 1.0053x over previous
.LBB0_1001:
	s_ashr_i32 s17, s16, 31
	s_lshl_b64 s[18:19], s[16:17], 19
	s_add_u32 s18, s92, s18
	s_addc_u32 s19, s93, s19
	s_and_b64 s[20:21], s[6:7], exec
	s_cselect_b32 s17, s19, s29
	s_cselect_b32 s51, s18, s28
	s_ashr_i32 s15, s14, 31
	s_lshl_b64 s[20:21], s[14:15], 19
	s_add_u32 s20, s41, s20
	s_addc_u32 s21, s42, s21
	s_and_b64 s[30:31], s[6:7], exec
	s_cselect_b32 s15, s21, s25
	s_cselect_b32 s52, s20, s24
	s_add_u32 s53, s24, 0x100
	s_addc_u32 s61, s25, 0
	s_add_u32 s24, s28, 0x40080
	s_addc_u32 s25, s29, 0
	s_mov_b32 s62, -2
	s_add_u32 s28, s24, 0xfffc0080
	s_addc_u32 s29, s25, -1
	s_add_i32 s63, 0, 0x10000
	s_cmp_eq_u32 s62, 12
	s_cselect_b32 s31, s17, s29
	s_cselect_b32 s30, s51, s28
	v_add_u32_e32 v140, s63, v143
	s_cselect_b32 s29, s15, s61
	s_cselect_b32 s28, s52, s53
	s_add_i32 s72, 0, 0x14000
	ds_read_b128 v[146:149], v140
	ds_read_b128 v[150:153], v140 offset:1024
	ds_read_b128 v[154:157], v140 offset:2048
	ds_read_b128 v[158:161], v140 offset:3072
	v_add_u32_e32 v140, s72, v143
	ds_read_b128 v[162:165], v140
	ds_read_b128 v[166:169], v140 offset:1024
	ds_read_b128 v[170:173], v140 offset:2048
	ds_read_b128 v[174:177], v140 offset:3072
	v_lshl_add_u64 v[140:141], s[24:25], 0, v[138:139]
	s_add_i32 m0, s23, 0xc000
	ds_read_b128 v[178:181], v145
	ds_read_b128 v[182:185], v145 offset:1024
	ds_read_b128 v[186:189], v145 offset:2048
	ds_read_b128 v[190:193], v145 offset:3072
	ds_read_b128 v[194:197], v145 offset:4096
	ds_read_b128 v[198:201], v145 offset:5120
	ds_read_b128 v[202:205], v145 offset:6144
	ds_read_b128 v[206:209], v145 offset:7168
	global_load_lds_dwordx4 v[140:141], off
	v_lshl_add_u64 v[140:141], s[24:25], 0, v[136:137]
	s_add_i32 m0, s23, 0xe000
	s_nop 0
	global_load_lds_dwordx4 v[140:141], off
	s_waitcnt vmcnt(8)
	s_waitcnt lgkmcnt(0)
	s_barrier
	s_setprio 1
	s_waitcnt lgkmcnt(0)
	v_mfma_f32_16x16x32_bf16 v[126:129], v[146:149], v[178:181], 0
	v_mfma_f32_16x16x32_bf16 v[122:125], v[154:157], v[178:181], 0
	v_mfma_f32_16x16x32_bf16 v[110:113], v[146:149], v[186:189], 0
	v_mfma_f32_16x16x32_bf16 v[106:109], v[154:157], v[186:189], 0
	v_mfma_f32_16x16x32_bf16 v[94:97], v[146:149], v[194:197], 0
	v_mfma_f32_16x16x32_bf16 v[90:93], v[154:157], v[194:197], 0
	v_mfma_f32_16x16x32_bf16 v[78:81], v[146:149], v[202:205], 0
	v_mfma_f32_16x16x32_bf16 v[74:77], v[154:157], v[202:205], 0
	v_mfma_f32_16x16x32_bf16 v[126:129], v[150:153], v[182:185], v[126:129]
	v_mfma_f32_16x16x32_bf16 v[122:125], v[158:161], v[182:185], v[122:125]
	v_mfma_f32_16x16x32_bf16 v[110:113], v[150:153], v[190:193], v[110:113]
	v_mfma_f32_16x16x32_bf16 v[106:109], v[158:161], v[190:193], v[106:109]
	v_mfma_f32_16x16x32_bf16 v[94:97], v[150:153], v[198:201], v[94:97]
	v_mfma_f32_16x16x32_bf16 v[90:93], v[158:161], v[198:201], v[90:93]
	v_mfma_f32_16x16x32_bf16 v[78:81], v[150:153], v[206:209], v[78:81]
	v_mfma_f32_16x16x32_bf16 v[74:77], v[158:161], v[206:209], v[74:77]
	s_setprio 0
	s_setprio 1
	v_mfma_f32_16x16x32_bf16 v[118:121], v[162:165], v[178:181], 0
	v_mfma_f32_16x16x32_bf16 v[114:117], v[170:173], v[178:181], 0
	v_mfma_f32_16x16x32_bf16 v[102:105], v[162:165], v[186:189], 0
	v_mfma_f32_16x16x32_bf16 v[98:101], v[170:173], v[186:189], 0
	v_mfma_f32_16x16x32_bf16 v[86:89], v[162:165], v[194:197], 0
	v_mfma_f32_16x16x32_bf16 v[82:85], v[170:173], v[194:197], 0
	v_mfma_f32_16x16x32_bf16 v[70:73], v[162:165], v[202:205], 0
	v_mfma_f32_16x16x32_bf16 v[66:69], v[170:173], v[202:205], 0
	v_mfma_f32_16x16x32_bf16 v[118:121], v[166:169], v[182:185], v[118:121]
	v_mfma_f32_16x16x32_bf16 v[114:117], v[174:177], v[182:185], v[114:117]
	v_mfma_f32_16x16x32_bf16 v[102:105], v[166:169], v[190:193], v[102:105]
	v_mfma_f32_16x16x32_bf16 v[98:101], v[174:177], v[190:193], v[98:101]
	v_mfma_f32_16x16x32_bf16 v[86:89], v[166:169], v[198:201], v[86:89]
	v_mfma_f32_16x16x32_bf16 v[82:85], v[174:177], v[198:201], v[82:85]
	v_mfma_f32_16x16x32_bf16 v[70:73], v[166:169], v[206:209], v[70:73]
	v_mfma_f32_16x16x32_bf16 v[66:69], v[174:177], v[206:209], v[66:69]
	s_setprio 0
	s_barrier
	s_add_i32 s63, s63, s40
	v_lshl_add_u64 v[140:141], s[28:29], 0, v[0:1]
	s_mov_b32 m0, s63
	ds_read_b128 v[178:181], v145 offset:16384
	ds_read_b128 v[182:185], v145 offset:17408
	ds_read_b128 v[186:189], v145 offset:18432
	ds_read_b128 v[190:193], v145 offset:19456
	ds_read_b128 v[194:197], v145 offset:20480
	ds_read_b128 v[198:201], v145 offset:21504
	ds_read_b128 v[202:205], v145 offset:22528
	ds_read_b128 v[206:209], v145 offset:23552
	global_load_lds_dwordx4 v[140:141], off
	s_add_i32 m0, s63, 0x2000
	s_add_u32 s70, s28, 0x40000
	v_lshl_add_u64 v[210:211], s[28:29], 0, v[134:135]
	s_addc_u32 s71, s29, 0
	s_add_i32 s63, s72, s40
	global_load_lds_dwordx4 v[210:211], off
	v_lshl_add_u64 v[212:213], s[70:71], 0, v[0:1]
	s_mov_b32 m0, s63
	v_lshl_add_u64 v[214:215], s[30:31], 0, v[132:133]
	global_load_lds_dwordx4 v[212:213], off
	v_lshl_add_u64 v[212:213], s[70:71], 0, v[134:135]
	s_add_i32 m0, s63, 0x2000
	s_nop 0
	global_load_lds_dwordx4 v[212:213], off
	v_lshl_add_u64 v[212:213], s[30:31], 0, v[130:131]
	s_mov_b32 m0, s23
	s_nop 0
	global_load_lds_dwordx4 v[212:213], off
	s_mov_b32 m0, s43
	s_nop 0
	global_load_lds_dwordx4 v[214:215], off
	s_waitcnt vmcnt(8)
	s_waitcnt lgkmcnt(0)
	s_barrier
	s_setprio 1
	s_waitcnt lgkmcnt(0)
	v_mfma_f32_16x16x32_bf16 v[62:65], v[146:149], v[178:181], 0
	v_mfma_f32_16x16x32_bf16 v[58:61], v[154:157], v[178:181], 0
	v_mfma_f32_16x16x32_bf16 v[46:49], v[146:149], v[186:189], 0
	v_mfma_f32_16x16x32_bf16 v[42:45], v[154:157], v[186:189], 0
	v_mfma_f32_16x16x32_bf16 v[30:33], v[146:149], v[194:197], 0
	v_mfma_f32_16x16x32_bf16 v[26:29], v[154:157], v[194:197], 0
	v_mfma_f32_16x16x32_bf16 v[14:17], v[146:149], v[202:205], 0
	v_mfma_f32_16x16x32_bf16 v[10:13], v[154:157], v[202:205], 0
	v_mfma_f32_16x16x32_bf16 v[62:65], v[150:153], v[182:185], v[62:65]
	v_mfma_f32_16x16x32_bf16 v[58:61], v[158:161], v[182:185], v[58:61]
	v_mfma_f32_16x16x32_bf16 v[46:49], v[150:153], v[190:193], v[46:49]
	v_mfma_f32_16x16x32_bf16 v[42:45], v[158:161], v[190:193], v[42:45]
	v_mfma_f32_16x16x32_bf16 v[30:33], v[150:153], v[198:201], v[30:33]
	v_mfma_f32_16x16x32_bf16 v[26:29], v[158:161], v[198:201], v[26:29]
	v_mfma_f32_16x16x32_bf16 v[14:17], v[150:153], v[206:209], v[14:17]
	v_mfma_f32_16x16x32_bf16 v[10:13], v[158:161], v[206:209], v[10:13]
	s_setprio 0
	s_setprio 1
	v_mfma_f32_16x16x32_bf16 v[54:57], v[162:165], v[178:181], 0
	v_mfma_f32_16x16x32_bf16 v[50:53], v[170:173], v[178:181], 0
	v_mfma_f32_16x16x32_bf16 v[38:41], v[162:165], v[186:189], 0
	v_mfma_f32_16x16x32_bf16 v[34:37], v[170:173], v[186:189], 0
	v_mfma_f32_16x16x32_bf16 v[22:25], v[162:165], v[194:197], 0
	v_mfma_f32_16x16x32_bf16 v[18:21], v[170:173], v[194:197], 0
	v_mfma_f32_16x16x32_bf16 v[6:9], v[162:165], v[202:205], 0
	v_mfma_f32_16x16x32_bf16 v[2:5], v[170:173], v[202:205], 0
	v_mfma_f32_16x16x32_bf16 v[54:57], v[166:169], v[182:185], v[54:57]
	v_mfma_f32_16x16x32_bf16 v[50:53], v[174:177], v[182:185], v[50:53]
	v_mfma_f32_16x16x32_bf16 v[38:41], v[166:169], v[190:193], v[38:41]
	v_mfma_f32_16x16x32_bf16 v[34:37], v[174:177], v[190:193], v[34:37]
	v_mfma_f32_16x16x32_bf16 v[22:25], v[166:169], v[198:201], v[22:25]
	v_mfma_f32_16x16x32_bf16 v[18:21], v[174:177], v[198:201], v[18:21]
	v_mfma_f32_16x16x32_bf16 v[6:9], v[166:169], v[206:209], v[6:9]
	v_mfma_f32_16x16x32_bf16 v[2:5], v[174:177], v[206:209], v[2:5]
	s_setprio 0
	s_barrier
	s_add_i32 s63, 0, 0x18000
	s_add_i32 s70, 0, 0x1c000
	v_add_u32_e32 v158, s63, v143
	v_add_u32_e32 v174, s70, v143
	ds_read_b128 v[146:149], v158
	ds_read_b128 v[150:153], v158 offset:1024
	ds_read_b128 v[154:157], v158 offset:2048
	ds_read_b128 v[158:161], v158 offset:3072
	ds_read_b128 v[162:165], v174
	ds_read_b128 v[166:169], v174 offset:1024
	ds_read_b128 v[170:173], v174 offset:2048
	ds_read_b128 v[174:177], v174 offset:3072
	s_add_u32 s30, s30, 0x40000
	s_addc_u32 s31, s31, 0
	s_mov_b32 m0, s44
	v_lshl_add_u64 v[216:217], s[30:31], 0, v[130:131]
	ds_read_b128 v[178:181], v145 offset:32768
	ds_read_b128 v[182:185], v145 offset:33792
	ds_read_b128 v[186:189], v145 offset:34816
	ds_read_b128 v[190:193], v145 offset:35840
	ds_read_b128 v[194:197], v145 offset:36864
	ds_read_b128 v[198:201], v145 offset:37888
	ds_read_b128 v[202:205], v145 offset:38912
	ds_read_b128 v[206:209], v145 offset:39936
	global_load_lds_dwordx4 v[216:217], off
	v_lshl_add_u64 v[216:217], s[30:31], 0, v[132:133]
	s_mov_b32 m0, s45
	s_nop 0
	global_load_lds_dwordx4 v[216:217], off
	s_waitcnt vmcnt(8)
	s_waitcnt lgkmcnt(0)
	s_barrier
	s_setprio 1
	s_waitcnt lgkmcnt(0)
	v_mfma_f32_16x16x32_bf16 v[126:129], v[146:149], v[178:181], v[126:129]
	v_mfma_f32_16x16x32_bf16 v[122:125], v[154:157], v[178:181], v[122:125]
	v_mfma_f32_16x16x32_bf16 v[110:113], v[146:149], v[186:189], v[110:113]
	v_mfma_f32_16x16x32_bf16 v[106:109], v[154:157], v[186:189], v[106:109]
	v_mfma_f32_16x16x32_bf16 v[94:97], v[146:149], v[194:197], v[94:97]
	v_mfma_f32_16x16x32_bf16 v[90:93], v[154:157], v[194:197], v[90:93]
	v_mfma_f32_16x16x32_bf16 v[78:81], v[146:149], v[202:205], v[78:81]
	v_mfma_f32_16x16x32_bf16 v[74:77], v[154:157], v[202:205], v[74:77]
	v_mfma_f32_16x16x32_bf16 v[126:129], v[150:153], v[182:185], v[126:129]
	v_mfma_f32_16x16x32_bf16 v[122:125], v[158:161], v[182:185], v[122:125]
	v_mfma_f32_16x16x32_bf16 v[110:113], v[150:153], v[190:193], v[110:113]
	v_mfma_f32_16x16x32_bf16 v[106:109], v[158:161], v[190:193], v[106:109]
	v_mfma_f32_16x16x32_bf16 v[94:97], v[150:153], v[198:201], v[94:97]
	v_mfma_f32_16x16x32_bf16 v[90:93], v[158:161], v[198:201], v[90:93]
	v_mfma_f32_16x16x32_bf16 v[78:81], v[150:153], v[206:209], v[78:81]
	v_mfma_f32_16x16x32_bf16 v[74:77], v[158:161], v[206:209], v[74:77]
	s_setprio 0
	s_setprio 1
	v_mfma_f32_16x16x32_bf16 v[118:121], v[162:165], v[178:181], v[118:121]
	v_mfma_f32_16x16x32_bf16 v[114:117], v[170:173], v[178:181], v[114:117]
	v_mfma_f32_16x16x32_bf16 v[102:105], v[162:165], v[186:189], v[102:105]
	v_mfma_f32_16x16x32_bf16 v[98:101], v[170:173], v[186:189], v[98:101]
	v_mfma_f32_16x16x32_bf16 v[86:89], v[162:165], v[194:197], v[86:89]
	v_mfma_f32_16x16x32_bf16 v[82:85], v[170:173], v[194:197], v[82:85]
	v_mfma_f32_16x16x32_bf16 v[70:73], v[162:165], v[202:205], v[70:73]
	v_mfma_f32_16x16x32_bf16 v[66:69], v[170:173], v[202:205], v[66:69]
	v_mfma_f32_16x16x32_bf16 v[118:121], v[166:169], v[182:185], v[118:121]
	v_mfma_f32_16x16x32_bf16 v[114:117], v[174:177], v[182:185], v[114:117]
	v_mfma_f32_16x16x32_bf16 v[102:105], v[166:169], v[190:193], v[102:105]
	v_mfma_f32_16x16x32_bf16 v[98:101], v[174:177], v[190:193], v[98:101]
	v_mfma_f32_16x16x32_bf16 v[86:89], v[166:169], v[198:201], v[86:89]
	v_mfma_f32_16x16x32_bf16 v[82:85], v[174:177], v[198:201], v[82:85]
	v_mfma_f32_16x16x32_bf16 v[70:73], v[166:169], v[206:209], v[70:73]
	v_mfma_f32_16x16x32_bf16 v[66:69], v[174:177], v[206:209], v[66:69]
	s_setprio 0
	s_barrier
	s_add_i32 s30, s63, s40
	v_lshl_add_u64 v[140:141], v[140:141], 0, s[76:77]
	s_mov_b32 m0, s30
	ds_read_b128 v[178:181], v145 offset:49152
	ds_read_b128 v[182:185], v145 offset:50176
	ds_read_b128 v[186:189], v145 offset:51200
	ds_read_b128 v[190:193], v145 offset:52224
	ds_read_b128 v[194:197], v145 offset:53248
	ds_read_b128 v[198:201], v145 offset:54272
	ds_read_b128 v[202:205], v145 offset:55296
	ds_read_b128 v[206:209], v145 offset:56320
	global_load_lds_dwordx4 v[140:141], off
	s_add_i32 m0, s30, 0x2000
	s_add_u32 s28, s28, 0x40080
	v_lshl_add_u64 v[140:141], v[210:211], 0, s[76:77]
	s_addc_u32 s29, s29, 0
	s_add_i32 s30, s70, s40
	global_load_lds_dwordx4 v[140:141], off
	v_lshl_add_u64 v[140:141], s[28:29], 0, v[0:1]
	s_mov_b32 m0, s30
	s_nop 0
	global_load_lds_dwordx4 v[140:141], off
	v_lshl_add_u64 v[140:141], s[28:29], 0, v[134:135]
	s_add_i32 m0, s30, 0x2000
	s_nop 0
	global_load_lds_dwordx4 v[140:141], off
	v_lshl_add_u64 v[140:141], v[212:213], 0, s[76:77]
	s_mov_b32 m0, s46
	s_nop 0
	global_load_lds_dwordx4 v[140:141], off
	v_lshl_add_u64 v[140:141], v[214:215], 0, s[76:77]
	s_mov_b32 m0, s47
	s_nop 0
	global_load_lds_dwordx4 v[140:141], off
	s_waitcnt vmcnt(8)
	s_waitcnt lgkmcnt(0)
	s_barrier
	s_setprio 1
	s_waitcnt lgkmcnt(0)
	v_mfma_f32_16x16x32_bf16 v[62:65], v[146:149], v[178:181], v[62:65]
	v_mfma_f32_16x16x32_bf16 v[58:61], v[154:157], v[178:181], v[58:61]
	v_mfma_f32_16x16x32_bf16 v[46:49], v[146:149], v[186:189], v[46:49]
	v_mfma_f32_16x16x32_bf16 v[42:45], v[154:157], v[186:189], v[42:45]
	v_mfma_f32_16x16x32_bf16 v[30:33], v[146:149], v[194:197], v[30:33]
	v_mfma_f32_16x16x32_bf16 v[26:29], v[154:157], v[194:197], v[26:29]
	v_mfma_f32_16x16x32_bf16 v[14:17], v[146:149], v[202:205], v[14:17]
	v_mfma_f32_16x16x32_bf16 v[10:13], v[154:157], v[202:205], v[10:13]
	v_mfma_f32_16x16x32_bf16 v[62:65], v[150:153], v[182:185], v[62:65]
	v_mfma_f32_16x16x32_bf16 v[58:61], v[158:161], v[182:185], v[58:61]
	v_mfma_f32_16x16x32_bf16 v[46:49], v[150:153], v[190:193], v[46:49]
	v_mfma_f32_16x16x32_bf16 v[42:45], v[158:161], v[190:193], v[42:45]
	v_mfma_f32_16x16x32_bf16 v[30:33], v[150:153], v[198:201], v[30:33]
	v_mfma_f32_16x16x32_bf16 v[26:29], v[158:161], v[198:201], v[26:29]
	v_mfma_f32_16x16x32_bf16 v[14:17], v[150:153], v[206:209], v[14:17]
	v_mfma_f32_16x16x32_bf16 v[10:13], v[158:161], v[206:209], v[10:13]
	s_setprio 0
	s_setprio 1
	v_mfma_f32_16x16x32_bf16 v[54:57], v[162:165], v[178:181], v[54:57]
	v_mfma_f32_16x16x32_bf16 v[50:53], v[170:173], v[178:181], v[50:53]
	v_mfma_f32_16x16x32_bf16 v[38:41], v[162:165], v[186:189], v[38:41]
	v_mfma_f32_16x16x32_bf16 v[34:37], v[170:173], v[186:189], v[34:37]
	v_mfma_f32_16x16x32_bf16 v[22:25], v[162:165], v[194:197], v[22:25]
	v_mfma_f32_16x16x32_bf16 v[18:21], v[170:173], v[194:197], v[18:21]
	v_mfma_f32_16x16x32_bf16 v[6:9], v[162:165], v[202:205], v[6:9]
	v_mfma_f32_16x16x32_bf16 v[2:5], v[170:173], v[202:205], v[2:5]
	v_mfma_f32_16x16x32_bf16 v[54:57], v[166:169], v[182:185], v[54:57]
	v_mfma_f32_16x16x32_bf16 v[50:53], v[174:177], v[182:185], v[50:53]
	v_mfma_f32_16x16x32_bf16 v[38:41], v[166:169], v[190:193], v[38:41]
	v_mfma_f32_16x16x32_bf16 v[34:37], v[174:177], v[190:193], v[34:37]
	v_mfma_f32_16x16x32_bf16 v[22:25], v[166:169], v[198:201], v[22:25]
	v_mfma_f32_16x16x32_bf16 v[18:21], v[174:177], v[198:201], v[18:21]
	v_mfma_f32_16x16x32_bf16 v[6:9], v[166:169], v[206:209], v[6:9]
	v_mfma_f32_16x16x32_bf16 v[2:5], v[174:177], v[206:209], v[2:5]
	s_setprio 0
	s_barrier
	s_add_i32 s62, s62, 2
	s_add_u32 s53, s53, 0x100
	s_addc_u32 s61, s61, 0
	s_add_u32 s24, s24, 0x100
	s_addc_u32 s25, s25, 0
	s_cmp_gt_u32 s62, 13
